# stacked: sample-unit MFMA skip + full-line LDS-DMA layout (QKV, up) + batched sample-state loads + priority on load segments
# speedup vs baseline: 1.0060x; 1.0060x over previous
; #define PG8_STAGE(bufoff, gbase, voff) do { _Pragma("unroll") for (int _i = 0; _i < 2; ++_i) \
;         __builtin_amdgcn_global_load_lds((const unsigned*)((const char*)(gbase) + (voff)[_i]), (LAS unsigned*)(lds + (bufoff) + ldsw + _i * 8192), 16, 0, 0); } while (0)
; #define PG8_LDA(dst, b, h) do { _Pragma("unroll") for (int m = 0; m < 4; ++m) _Pragma("unroll") for (int k = 0; k < 2; ++k) dst[m][k] = *(const LAS bf16x8*)(lds + PG8_SA(b, h) + aoff + m * 2048 + k * 1024); } while (0)
; #define PG8_LDB(dst, b, h) do { _Pragma("unroll") for (int n = 0; n < 2; ++n) _Pragma("unroll") for (int k = 0; k < 2; ++k) dst[n][k] = *(const LAS bf16x8*)(lds + PG8_SB(b, h) + boff + n * 2048 + k * 1024); } while (0)
; #define PG8_MMA(ai, bj, At, Bt) do { __builtin_amdgcn_s_setprio(1); _Pragma("unroll") for (int m = 0; m < 4; ++m) _Pragma("unroll") for (int n = 0; n < 2; ++n) _Pragma("unroll") for (int k = 0; k < 2; ++k) \
;         acc[ai][bj][m][n] = __builtin_amdgcn_mfma_f32_16x16x32_bf16(Bt[n][k], At[m][k], acc[ai][bj][m][n], 0, 0, 0); __builtin_amdgcn_s_setprio(0); } while (0)
; #define PG8_WAIT_V(n) asm volatile("s_waitcnt vmcnt(" #n ")" ::: "memory")
; #define PG8_WAIT_L(n) asm volatile("s_waitcnt lgkmcnt(" #n ")" ::: "memory")
; #define PG8_BAR __builtin_amdgcn_s_barrier()
; #define PG8_SCHED __builtin_amdgcn_sched_barrier(0)
; template <class Epi, class Sched>
; __device__ __forceinline__ void gemm_phase(LAS unsigned char* lds, const GemmP g, const Sched& S, const Epi& E, int tid) {
;     ...
;             const bool last = (t == nt - 2);
;             const char* a1 = cA + (size_t)(t + 1) * kstep;
;             const char* a2 = last ? nA : cA + (size_t)(t + 2) * kstep; const char* b2 = last ? nB : cB + (size_t)(t + 2) * kstep;
;             const char* a3 = a2 + kstep; const char* b3 = b2 + kstep;
;             PG8_LDB(B0, 0, 0); PG8_LDB(B1, 0, 1); PG8_SCHED; PG8_LDA(At, 0, 0); PG8_STAGE(PG8_SA(1, 1), a1 + hstepA, voffA);
;             PG8_WAIT_V(8); PG8_WAIT_L(0); PG8_BAR; PG8_MMA(0, 0, At, B0); PG8_MMA(0, 1, At, B1); PG8_BAR; PG8_SCHED;
;             PG8_LDA(At, 0, 1); PG8_STAGE(PG8_SB(0, 0), b2, voffB); PG8_STAGE(PG8_SB(0, 1), b2 + hstepB, voffB); PG8_STAGE(PG8_SA(0, 0), a2, voffA);
.LBB0_166:
	s_setprio 1
	ds_read_b128 v[144:147], v157
	ds_read_b128 v[148:151], v228
	ds_read_b128 v[152:155], v157 offset:2048
	ds_read_b128 v[162:165], v228 offset:2048
	ds_read_b128 v[166:169], v158
	ds_read_b128 v[170:173], v229
	ds_read_b128 v[174:177], v158 offset:2048
	ds_read_b128 v[178:181], v229 offset:2048
	s_add_u32 s44, s4, 0xfffc0080
	s_addc_u32 s45, s5, -1
	s_cmp_eq_u32 s73, 12
	s_cselect_b32 s47, s37, s45
	s_cselect_b32 s46, s36, s44
	s_cselect_b32 s45, s39, s72
	s_cselect_b32 s44, s38, s71
	v_lshl_add_u64 v[214:215], s[4:5], 0, v[138:139]
	s_add_i32 m0, s53, 0xc000
	ds_read_b128 v[182:185], v159
	ds_read_b128 v[186:189], v226
	ds_read_b128 v[190:193], v159 offset:2048
	ds_read_b128 v[194:197], v226 offset:2048
	ds_read_b128 v[198:201], v159 offset:4096
	ds_read_b128 v[202:205], v226 offset:4096
	ds_read_b128 v[206:209], v159 offset:6144
	ds_read_b128 v[210:213], v226 offset:6144
	global_load_lds_dwordx4 v[214:215], off
	v_lshl_add_u64 v[214:215], s[4:5], 0, v[136:137]
	s_add_i32 m0, s53, 0xe000
	s_nop 0
	global_load_lds_dwordx4 v[214:215], off
	s_cmp_eq_u32 s73, -2
	s_cbranch_scc1 .Lfirstit_1
	s_waitcnt vmcnt(8)
.Lfirstit_1:
	s_waitcnt lgkmcnt(0)
	s_setprio 0
	s_barrier
	s_waitcnt lgkmcnt(0)
	v_mfma_f32_16x16x32_bf16 v[124:127], v[144:147], v[182:185], v[124:127]
	v_mfma_f32_16x16x32_bf16 v[120:123], v[152:155], v[182:185], v[120:123]
	v_mfma_f32_16x16x32_bf16 v[108:111], v[144:147], v[190:193], v[108:111]
	v_mfma_f32_16x16x32_bf16 v[104:107], v[152:155], v[190:193], v[104:107]
	v_mfma_f32_16x16x32_bf16 v[92:95], v[144:147], v[198:201], v[92:95]
	v_mfma_f32_16x16x32_bf16 v[88:91], v[152:155], v[198:201], v[88:91]
	v_mfma_f32_16x16x32_bf16 v[76:79], v[144:147], v[206:209], v[76:79]
	v_mfma_f32_16x16x32_bf16 v[72:75], v[152:155], v[206:209], v[72:75]
	v_mfma_f32_16x16x32_bf16 v[124:127], v[148:151], v[186:189], v[124:127]
	v_mfma_f32_16x16x32_bf16 v[120:123], v[162:165], v[186:189], v[120:123]
	v_mfma_f32_16x16x32_bf16 v[108:111], v[148:151], v[194:197], v[108:111]
	v_mfma_f32_16x16x32_bf16 v[104:107], v[162:165], v[194:197], v[104:107]
	v_mfma_f32_16x16x32_bf16 v[92:95], v[148:151], v[202:205], v[92:95]
	v_mfma_f32_16x16x32_bf16 v[88:91], v[162:165], v[202:205], v[88:91]
	v_mfma_f32_16x16x32_bf16 v[76:79], v[148:151], v[210:213], v[76:79]
	v_mfma_f32_16x16x32_bf16 v[72:75], v[162:165], v[210:213], v[72:75]
	v_mfma_f32_16x16x32_bf16 v[116:119], v[166:169], v[182:185], v[116:119]
	v_mfma_f32_16x16x32_bf16 v[112:115], v[174:177], v[182:185], v[112:115]
	v_mfma_f32_16x16x32_bf16 v[100:103], v[166:169], v[190:193], v[100:103]
	v_mfma_f32_16x16x32_bf16 v[96:99], v[174:177], v[190:193], v[96:99]
	v_mfma_f32_16x16x32_bf16 v[84:87], v[166:169], v[198:201], v[84:87]
	v_mfma_f32_16x16x32_bf16 v[80:83], v[174:177], v[198:201], v[80:83]
	v_mfma_f32_16x16x32_bf16 v[68:71], v[166:169], v[206:209], v[68:71]
	v_mfma_f32_16x16x32_bf16 v[64:67], v[174:177], v[206:209], v[64:67]
	v_mfma_f32_16x16x32_bf16 v[116:119], v[170:173], v[186:189], v[116:119]
	v_mfma_f32_16x16x32_bf16 v[112:115], v[178:181], v[186:189], v[112:115]
	v_mfma_f32_16x16x32_bf16 v[100:103], v[170:173], v[194:197], v[100:103]
	v_mfma_f32_16x16x32_bf16 v[96:99], v[178:181], v[194:197], v[96:99]
	v_mfma_f32_16x16x32_bf16 v[84:87], v[170:173], v[202:205], v[84:87]
	v_mfma_f32_16x16x32_bf16 v[80:83], v[178:181], v[202:205], v[80:83]
	v_mfma_f32_16x16x32_bf16 v[68:71], v[170:173], v[210:213], v[68:71]
	v_mfma_f32_16x16x32_bf16 v[64:67], v[178:181], v[210:213], v[64:67]
	s_barrier
	s_setprio 1
	s_add_i32 s74, s67, s52
	v_lshl_add_u64 v[214:215], s[44:45], 0, v[130:131]
	s_mov_b32 m0, s74
	ds_read_b128 v[182:185], v159 offset:16384
	ds_read_b128 v[186:189], v226 offset:16384
	ds_read_b128 v[190:193], v159 offset:18432
	ds_read_b128 v[194:197], v226 offset:18432
	ds_read_b128 v[198:201], v159 offset:20480
	ds_read_b128 v[202:205], v226 offset:20480
	ds_read_b128 v[206:209], v159 offset:22528
	ds_read_b128 v[210:213], v226 offset:22528
	global_load_lds_dwordx4 v[214:215], off
	s_add_i32 m0, s74, 0x2000
	s_add_u32 s74, s44, 0x40000
	v_lshl_add_u64 v[216:217], s[44:45], 0, v[134:135]
	s_addc_u32 s75, s45, 0
	s_add_i32 s76, s68, s52
	global_load_lds_dwordx4 v[216:217], off
	v_lshl_add_u64 v[218:219], s[74:75], 0, v[130:131]
	s_mov_b32 m0, s76
	v_lshl_add_u64 v[220:221], s[46:47], 0, v[132:133]
	global_load_lds_dwordx4 v[218:219], off
	v_lshl_add_u64 v[218:219], s[74:75], 0, v[134:135]
	s_add_i32 m0, s76, 0x2000
	s_nop 0
	global_load_lds_dwordx4 v[218:219], off
	v_lshl_add_u64 v[218:219], s[46:47], 0, v[128:129]
	s_mov_b32 m0, s53
	s_nop 0
	global_load_lds_dwordx4 v[218:219], off
	s_mov_b32 m0, s54
	s_nop 0
	global_load_lds_dwordx4 v[220:221], off
	s_waitcnt vmcnt(8)
	s_waitcnt lgkmcnt(0)
	s_setprio 0
	s_barrier
; #define PG8_STAGE(bufoff, gbase, voff) do { _Pragma("unroll") for (int _i = 0; _i < 2; ++_i) \
;         __builtin_amdgcn_global_load_lds((const unsigned*)((const char*)(gbase) + (voff)[_i]), (LAS unsigned*)(lds + (bufoff) + ldsw + _i * 8192), 16, 0, 0); } while (0)
; #define PG8_LDA(dst, b, h) do { _Pragma("unroll") for (int m = 0; m < 4; ++m) _Pragma("unroll") for (int k = 0; k < 2; ++k) dst[m][k] = *(const LAS bf16x8*)(lds + PG8_SA(b, h) + aoff + m * 2048 + k * 1024); } while (0)
; #define PG8_LDB(dst, b, h) do { _Pragma("unroll") for (int n = 0; n < 2; ++n) _Pragma("unroll") for (int k = 0; k < 2; ++k) dst[n][k] = *(const LAS bf16x8*)(lds + PG8_SB(b, h) + boff + n * 2048 + k * 1024); } while (0)
; #define PG8_MMA(ai, bj, At, Bt) do { __builtin_amdgcn_s_setprio(1); _Pragma("unroll") for (int m = 0; m < 4; ++m) _Pragma("unroll") for (int n = 0; n < 2; ++n) _Pragma("unroll") for (int k = 0; k < 2; ++k) \
;         acc[ai][bj][m][n] = __builtin_amdgcn_mfma_f32_16x16x32_bf16(Bt[n][k], At[m][k], acc[ai][bj][m][n], 0, 0, 0); __builtin_amdgcn_s_setprio(0); } while (0)
; #define PG8_WAIT_V(n) asm volatile("s_waitcnt vmcnt(" #n ")" ::: "memory")
; #define PG8_WAIT_L(n) asm volatile("s_waitcnt lgkmcnt(" #n ")" ::: "memory")
; #define PG8_BAR __builtin_amdgcn_s_barrier()
; #define PG8_SCHED __builtin_amdgcn_sched_barrier(0)
; template <class Epi, class Sched>
; __device__ __forceinline__ void gemm_phase(LAS unsigned char* lds, const GemmP g, const Sched& S, const Epi& E, int tid) {
;     ...
;             PG8_WAIT_V(8); PG8_WAIT_L(0); PG8_BAR; PG8_MMA(0, 0, At, B0); PG8_MMA(0, 1, At, B1); PG8_BAR; PG8_SCHED;
;             PG8_LDA(At, 0, 1); PG8_STAGE(PG8_SB(0, 0), b2, voffB); PG8_STAGE(PG8_SB(0, 1), b2 + hstepB, voffB); PG8_STAGE(PG8_SA(0, 0), a2, voffA);
;             PG8_WAIT_V(8); PG8_WAIT_L(0); PG8_BAR; PG8_MMA(1, 0, At, B0); PG8_MMA(1, 1, At, B1); PG8_BAR; PG8_SCHED;
;             PG8_LDB(B0, 1, 0); PG8_LDB(B1, 1, 1); PG8_SCHED; PG8_LDA(At, 1, 0); PG8_STAGE(PG8_SA(0, 1), a2 + hstepA, voffA);
;             PG8_WAIT_V(8); PG8_WAIT_L(0); PG8_BAR; PG8_MMA(0, 0, At, B0); PG8_MMA(0, 1, At, B1); PG8_BAR; PG8_SCHED;
	s_waitcnt lgkmcnt(0)
	v_mfma_f32_16x16x32_bf16 v[60:63], v[144:147], v[182:185], v[60:63]
	v_mfma_f32_16x16x32_bf16 v[56:59], v[152:155], v[182:185], v[56:59]
	v_mfma_f32_16x16x32_bf16 v[44:47], v[144:147], v[190:193], v[44:47]
	v_mfma_f32_16x16x32_bf16 v[40:43], v[152:155], v[190:193], v[40:43]
	v_mfma_f32_16x16x32_bf16 v[28:31], v[144:147], v[198:201], v[28:31]
	v_mfma_f32_16x16x32_bf16 v[24:27], v[152:155], v[198:201], v[24:27]
	v_mfma_f32_16x16x32_bf16 v[12:15], v[144:147], v[206:209], v[12:15]
	v_mfma_f32_16x16x32_bf16 v[8:11], v[152:155], v[206:209], v[8:11]
	v_mfma_f32_16x16x32_bf16 v[60:63], v[148:151], v[186:189], v[60:63]
	v_mfma_f32_16x16x32_bf16 v[56:59], v[162:165], v[186:189], v[56:59]
	v_mfma_f32_16x16x32_bf16 v[44:47], v[148:151], v[194:197], v[44:47]
	v_mfma_f32_16x16x32_bf16 v[40:43], v[162:165], v[194:197], v[40:43]
	v_mfma_f32_16x16x32_bf16 v[28:31], v[148:151], v[202:205], v[28:31]
	v_mfma_f32_16x16x32_bf16 v[24:27], v[162:165], v[202:205], v[24:27]
	v_mfma_f32_16x16x32_bf16 v[12:15], v[148:151], v[210:213], v[12:15]
	v_mfma_f32_16x16x32_bf16 v[8:11], v[162:165], v[210:213], v[8:11]
	v_mfma_f32_16x16x32_bf16 v[52:55], v[166:169], v[182:185], v[52:55]
	v_mfma_f32_16x16x32_bf16 v[48:51], v[174:177], v[182:185], v[48:51]
	v_mfma_f32_16x16x32_bf16 v[36:39], v[166:169], v[190:193], v[36:39]
	v_mfma_f32_16x16x32_bf16 v[32:35], v[174:177], v[190:193], v[32:35]
	v_mfma_f32_16x16x32_bf16 v[20:23], v[166:169], v[198:201], v[20:23]
	v_mfma_f32_16x16x32_bf16 v[16:19], v[174:177], v[198:201], v[16:19]
	v_mfma_f32_16x16x32_bf16 v[4:7], v[166:169], v[206:209], v[4:7]
	v_mfma_f32_16x16x32_bf16 v[0:3], v[174:177], v[206:209], v[0:3]
	v_mfma_f32_16x16x32_bf16 v[52:55], v[170:173], v[186:189], v[52:55]
	v_mfma_f32_16x16x32_bf16 v[48:51], v[178:181], v[186:189], v[48:51]
	v_mfma_f32_16x16x32_bf16 v[36:39], v[170:173], v[194:197], v[36:39]
	v_mfma_f32_16x16x32_bf16 v[32:35], v[178:181], v[194:197], v[32:35]
	v_mfma_f32_16x16x32_bf16 v[20:23], v[170:173], v[202:205], v[20:23]
	v_mfma_f32_16x16x32_bf16 v[16:19], v[178:181], v[202:205], v[16:19]
	v_mfma_f32_16x16x32_bf16 v[4:7], v[170:173], v[210:213], v[4:7]
	v_mfma_f32_16x16x32_bf16 v[0:3], v[178:181], v[210:213], v[0:3]
	s_barrier
	s_setprio 1
	s_add_i32 s74, 0, 0x18000
	s_add_i32 s75, 0, 0x1c000
	v_add_u32_e32 v162, s74, v156
	v_add_u32_e32 v178, s75, v156
	v_add_u32_e32 v230, s74, v227
	v_add_u32_e32 v231, s75, v227
	ds_read_b128 v[144:147], v162
	ds_read_b128 v[148:151], v230
	ds_read_b128 v[152:155], v162 offset:2048
	ds_read_b128 v[162:165], v230 offset:2048
	ds_read_b128 v[166:169], v178
	ds_read_b128 v[170:173], v231
	ds_read_b128 v[174:177], v178 offset:2048
	ds_read_b128 v[178:181], v231 offset:2048
	s_add_u32 s46, s46, 0x40000
	s_addc_u32 s47, s47, 0
	s_mov_b32 m0, s55
	v_lshl_add_u64 v[222:223], s[46:47], 0, v[128:129]
	ds_read_b128 v[182:185], v159 offset:32768
	ds_read_b128 v[186:189], v226 offset:32768
	ds_read_b128 v[190:193], v159 offset:34816
	ds_read_b128 v[194:197], v226 offset:34816
	ds_read_b128 v[198:201], v159 offset:36864
	ds_read_b128 v[202:205], v226 offset:36864
	ds_read_b128 v[206:209], v159 offset:38912
	ds_read_b128 v[210:213], v226 offset:38912
	global_load_lds_dwordx4 v[222:223], off
	v_lshl_add_u64 v[222:223], s[46:47], 0, v[132:133]
	s_mov_b32 m0, s56
	s_nop 0
	global_load_lds_dwordx4 v[222:223], off
	s_waitcnt vmcnt(8)
	s_waitcnt lgkmcnt(0)
	s_setprio 0
	s_barrier
	s_waitcnt lgkmcnt(0)
	v_mfma_f32_16x16x32_bf16 v[124:127], v[144:147], v[182:185], v[124:127]
	v_mfma_f32_16x16x32_bf16 v[120:123], v[152:155], v[182:185], v[120:123]
	v_mfma_f32_16x16x32_bf16 v[108:111], v[144:147], v[190:193], v[108:111]
	v_mfma_f32_16x16x32_bf16 v[104:107], v[152:155], v[190:193], v[104:107]
	v_mfma_f32_16x16x32_bf16 v[92:95], v[144:147], v[198:201], v[92:95]
	v_mfma_f32_16x16x32_bf16 v[88:91], v[152:155], v[198:201], v[88:91]
	v_mfma_f32_16x16x32_bf16 v[76:79], v[144:147], v[206:209], v[76:79]
	v_mfma_f32_16x16x32_bf16 v[72:75], v[152:155], v[206:209], v[72:75]
	v_mfma_f32_16x16x32_bf16 v[124:127], v[148:151], v[186:189], v[124:127]
	v_mfma_f32_16x16x32_bf16 v[120:123], v[162:165], v[186:189], v[120:123]
	v_mfma_f32_16x16x32_bf16 v[108:111], v[148:151], v[194:197], v[108:111]
	v_mfma_f32_16x16x32_bf16 v[104:107], v[162:165], v[194:197], v[104:107]
	v_mfma_f32_16x16x32_bf16 v[92:95], v[148:151], v[202:205], v[92:95]
	v_mfma_f32_16x16x32_bf16 v[88:91], v[162:165], v[202:205], v[88:91]
	v_mfma_f32_16x16x32_bf16 v[76:79], v[148:151], v[210:213], v[76:79]
	v_mfma_f32_16x16x32_bf16 v[72:75], v[162:165], v[210:213], v[72:75]
	v_mfma_f32_16x16x32_bf16 v[116:119], v[166:169], v[182:185], v[116:119]
	v_mfma_f32_16x16x32_bf16 v[112:115], v[174:177], v[182:185], v[112:115]
	v_mfma_f32_16x16x32_bf16 v[100:103], v[166:169], v[190:193], v[100:103]
	v_mfma_f32_16x16x32_bf16 v[96:99], v[174:177], v[190:193], v[96:99]
	v_mfma_f32_16x16x32_bf16 v[84:87], v[166:169], v[198:201], v[84:87]
	v_mfma_f32_16x16x32_bf16 v[80:83], v[174:177], v[198:201], v[80:83]
	v_mfma_f32_16x16x32_bf16 v[68:71], v[166:169], v[206:209], v[68:71]
	v_mfma_f32_16x16x32_bf16 v[64:67], v[174:177], v[206:209], v[64:67]
	v_mfma_f32_16x16x32_bf16 v[116:119], v[170:173], v[186:189], v[116:119]
	v_mfma_f32_16x16x32_bf16 v[112:115], v[178:181], v[186:189], v[112:115]
	v_mfma_f32_16x16x32_bf16 v[100:103], v[170:173], v[194:197], v[100:103]
	v_mfma_f32_16x16x32_bf16 v[96:99], v[178:181], v[194:197], v[96:99]
	v_mfma_f32_16x16x32_bf16 v[84:87], v[170:173], v[202:205], v[84:87]
	v_mfma_f32_16x16x32_bf16 v[80:83], v[178:181], v[202:205], v[80:83]
	v_mfma_f32_16x16x32_bf16 v[68:71], v[170:173], v[210:213], v[68:71]
	v_mfma_f32_16x16x32_bf16 v[64:67], v[178:181], v[210:213], v[64:67]
	s_barrier
; #define PG8_STAGE(bufoff, gbase, voff) do { _Pragma("unroll") for (int _i = 0; _i < 2; ++_i) \
;         __builtin_amdgcn_global_load_lds((const unsigned*)((const char*)(gbase) + (voff)[_i]), (LAS unsigned*)(lds + (bufoff) + ldsw + _i * 8192), 16, 0, 0); } while (0)
; #define PG8_LDA(dst, b, h) do { _Pragma("unroll") for (int m = 0; m < 4; ++m) _Pragma("unroll") for (int k = 0; k < 2; ++k) dst[m][k] = *(const LAS bf16x8*)(lds + PG8_SA(b, h) + aoff + m * 2048 + k * 1024); } while (0)
; #define PG8_MMA(ai, bj, At, Bt) do { __builtin_amdgcn_s_setprio(1); _Pragma("unroll") for (int m = 0; m < 4; ++m) _Pragma("unroll") for (int n = 0; n < 2; ++n) _Pragma("unroll") for (int k = 0; k < 2; ++k) \
;         acc[ai][bj][m][n] = __builtin_amdgcn_mfma_f32_16x16x32_bf16(Bt[n][k], At[m][k], acc[ai][bj][m][n], 0, 0, 0); __builtin_amdgcn_s_setprio(0); } while (0)
; #define PG8_WAIT_V(n) asm volatile("s_waitcnt vmcnt(" #n ")" ::: "memory")
; #define PG8_WAIT_L(n) asm volatile("s_waitcnt lgkmcnt(" #n ")" ::: "memory")
; #define PG8_BAR __builtin_amdgcn_s_barrier()
; #define PG8_SCHED __builtin_amdgcn_sched_barrier(0)
; template <class Epi, class Sched>
; __device__ __forceinline__ void gemm_phase(LAS unsigned char* lds, const GemmP g, const Sched& S, const Epi& E, int tid) {
;     ...
;             PG8_LDA(At, 1, 1); PG8_STAGE(PG8_SB(1, 0), b3, voffB); PG8_STAGE(PG8_SB(1, 1), b3 + hstepB, voffB); PG8_STAGE(PG8_SA(1, 0), a3, voffA);
;             PG8_WAIT_V(8); PG8_WAIT_L(0); PG8_BAR; PG8_MMA(1, 0, At, B0); PG8_MMA(1, 1, At, B1); PG8_BAR; PG8_SCHED;
;         }
;         if (wr == 0) PG8_BAR;
	s_setprio 1
	s_add_i32 s46, s74, s52
	v_lshl_add_u64 v[214:215], v[214:215], 0, s[14:15]
	s_mov_b32 m0, s46
	ds_read_b128 v[182:185], v159 offset:49152
	ds_read_b128 v[186:189], v226 offset:49152
	ds_read_b128 v[190:193], v159 offset:51200
	ds_read_b128 v[194:197], v226 offset:51200
	ds_read_b128 v[198:201], v159 offset:53248
	ds_read_b128 v[202:205], v226 offset:53248
	ds_read_b128 v[206:209], v159 offset:55296
	ds_read_b128 v[210:213], v226 offset:55296
	global_load_lds_dwordx4 v[214:215], off
	s_add_i32 m0, s46, 0x2000
	s_add_u32 s44, s44, 0x40080
	v_lshl_add_u64 v[214:215], v[216:217], 0, s[14:15]
	s_addc_u32 s45, s45, 0
	s_add_i32 s46, s75, s52
	global_load_lds_dwordx4 v[214:215], off
	v_lshl_add_u64 v[214:215], s[44:45], 0, v[130:131]
	s_mov_b32 m0, s46
	s_nop 0
	global_load_lds_dwordx4 v[214:215], off
	v_lshl_add_u64 v[214:215], s[44:45], 0, v[134:135]
	s_add_i32 m0, s46, 0x2000
	s_nop 0
	global_load_lds_dwordx4 v[214:215], off
	v_lshl_add_u64 v[214:215], v[218:219], 0, s[14:15]
	s_mov_b32 m0, s62
	s_nop 0
	global_load_lds_dwordx4 v[214:215], off
	v_lshl_add_u64 v[214:215], v[220:221], 0, s[14:15]
	s_mov_b32 m0, s63
	s_nop 0
	global_load_lds_dwordx4 v[214:215], off
	s_waitcnt vmcnt(8)
	s_waitcnt lgkmcnt(0)
	s_setprio 0
	s_barrier
	s_waitcnt lgkmcnt(0)
	v_mfma_f32_16x16x32_bf16 v[60:63], v[144:147], v[182:185], v[60:63]
	v_mfma_f32_16x16x32_bf16 v[56:59], v[152:155], v[182:185], v[56:59]
	v_mfma_f32_16x16x32_bf16 v[44:47], v[144:147], v[190:193], v[44:47]
	v_mfma_f32_16x16x32_bf16 v[40:43], v[152:155], v[190:193], v[40:43]
	v_mfma_f32_16x16x32_bf16 v[28:31], v[144:147], v[198:201], v[28:31]
	v_mfma_f32_16x16x32_bf16 v[24:27], v[152:155], v[198:201], v[24:27]
	v_mfma_f32_16x16x32_bf16 v[12:15], v[144:147], v[206:209], v[12:15]
	v_mfma_f32_16x16x32_bf16 v[8:11], v[152:155], v[206:209], v[8:11]
	v_mfma_f32_16x16x32_bf16 v[60:63], v[148:151], v[186:189], v[60:63]
	v_mfma_f32_16x16x32_bf16 v[56:59], v[162:165], v[186:189], v[56:59]
	v_mfma_f32_16x16x32_bf16 v[44:47], v[148:151], v[194:197], v[44:47]
	v_mfma_f32_16x16x32_bf16 v[40:43], v[162:165], v[194:197], v[40:43]
	v_mfma_f32_16x16x32_bf16 v[28:31], v[148:151], v[202:205], v[28:31]
	v_mfma_f32_16x16x32_bf16 v[24:27], v[162:165], v[202:205], v[24:27]
	v_mfma_f32_16x16x32_bf16 v[12:15], v[148:151], v[210:213], v[12:15]
	v_mfma_f32_16x16x32_bf16 v[8:11], v[162:165], v[210:213], v[8:11]
	v_mfma_f32_16x16x32_bf16 v[52:55], v[166:169], v[182:185], v[52:55]
	v_mfma_f32_16x16x32_bf16 v[48:51], v[174:177], v[182:185], v[48:51]
	v_mfma_f32_16x16x32_bf16 v[36:39], v[166:169], v[190:193], v[36:39]
	v_mfma_f32_16x16x32_bf16 v[32:35], v[174:177], v[190:193], v[32:35]
	v_mfma_f32_16x16x32_bf16 v[20:23], v[166:169], v[198:201], v[20:23]
	v_mfma_f32_16x16x32_bf16 v[16:19], v[174:177], v[198:201], v[16:19]
	v_mfma_f32_16x16x32_bf16 v[4:7], v[166:169], v[206:209], v[4:7]
	v_mfma_f32_16x16x32_bf16 v[0:3], v[174:177], v[206:209], v[0:3]
	v_mfma_f32_16x16x32_bf16 v[52:55], v[170:173], v[186:189], v[52:55]
	v_mfma_f32_16x16x32_bf16 v[48:51], v[178:181], v[186:189], v[48:51]
	v_mfma_f32_16x16x32_bf16 v[36:39], v[170:173], v[194:197], v[36:39]
	v_mfma_f32_16x16x32_bf16 v[32:35], v[178:181], v[194:197], v[32:35]
	v_mfma_f32_16x16x32_bf16 v[20:23], v[170:173], v[202:205], v[20:23]
	v_mfma_f32_16x16x32_bf16 v[16:19], v[178:181], v[202:205], v[16:19]
	v_mfma_f32_16x16x32_bf16 v[4:7], v[170:173], v[210:213], v[4:7]
	v_mfma_f32_16x16x32_bf16 v[0:3], v[178:181], v[210:213], v[0:3]
	s_barrier
	s_add_i32 s73, s73, 2
	s_add_u32 s71, s71, 0x100
	s_addc_u32 s72, s72, 0
	s_add_u32 s4, s4, 0x100
	s_addc_u32 s5, s5, 0
	s_cmp_gt_u32 s73, 13
	s_cbranch_scc0 .LBB0_166
	s_and_b64 vcc, exec, s[16:17]
	s_cbranch_vccz .LBB0_169
	s_barrier

; #define PG8_STAGE(bufoff, gbase, voff) do { _Pragma("unroll") for (int _i = 0; _i < 2; ++_i) \
;         __builtin_amdgcn_global_load_lds((const unsigned*)((const char*)(gbase) + (voff)[_i]), (LAS unsigned*)(lds + (bufoff) + ldsw + _i * 8192), 16, 0, 0); } while (0)
; #define PG8_LDA(dst, b, h) do { _Pragma("unroll") for (int m = 0; m < 4; ++m) _Pragma("unroll") for (int k = 0; k < 2; ++k) dst[m][k] = *(const LAS bf16x8*)(lds + PG8_SA(b, h) + aoff + m * 2048 + k * 1024); } while (0)
; #define PG8_LDB(dst, b, h) do { _Pragma("unroll") for (int n = 0; n < 2; ++n) _Pragma("unroll") for (int k = 0; k < 2; ++k) dst[n][k] = *(const LAS bf16x8*)(lds + PG8_SB(b, h) + boff + n * 2048 + k * 1024); } while (0)
; #define PG8_MMA(ai, bj, At, Bt) do { __builtin_amdgcn_s_setprio(1); _Pragma("unroll") for (int m = 0; m < 4; ++m) _Pragma("unroll") for (int n = 0; n < 2; ++n) _Pragma("unroll") for (int k = 0; k < 2; ++k) \
;         acc[ai][bj][m][n] = __builtin_amdgcn_mfma_f32_16x16x32_bf16(Bt[n][k], At[m][k], acc[ai][bj][m][n], 0, 0, 0); __builtin_amdgcn_s_setprio(0); } while (0)
; #define PG8_WAIT_V(n) asm volatile("s_waitcnt vmcnt(" #n ")" ::: "memory")
; #define PG8_WAIT_L(n) asm volatile("s_waitcnt lgkmcnt(" #n ")" ::: "memory")
; #define PG8_BAR __builtin_amdgcn_s_barrier()
; #define PG8_SCHED __builtin_amdgcn_sched_barrier(0)
; template <class Epi, class Sched>
; __device__ __forceinline__ void gemm_phase(LAS unsigned char* lds, const GemmP g, const Sched& S, const Epi& E, int tid) {
;     ...
;         for (int t = 0; t < nt; t += 2) {
;             const bool last = (t == nt - 2);
;             const char* a1 = cA + (size_t)(t + 1) * kstep;
;             const char* a2 = last ? nA : cA + (size_t)(t + 2) * kstep; const char* b2 = last ? nB : cB + (size_t)(t + 2) * kstep;
;             const char* a3 = a2 + kstep; const char* b3 = b2 + kstep;
;             PG8_LDB(B0, 0, 0); PG8_LDB(B1, 0, 1); PG8_SCHED; PG8_LDA(At, 0, 0); PG8_STAGE(PG8_SA(1, 1), a1 + hstepA, voffA);
;             PG8_WAIT_V(8); PG8_WAIT_L(0); PG8_BAR; PG8_MMA(0, 0, At, B0); PG8_MMA(0, 1, At, B1); PG8_BAR; PG8_SCHED;
;             PG8_LDA(At, 0, 1); PG8_STAGE(PG8_SB(0, 0), b2, voffB); PG8_STAGE(PG8_SB(0, 1), b2 + hstepB, voffB); PG8_STAGE(PG8_SA(0, 0), a2, voffA);
;             PG8_WAIT_V(8); PG8_WAIT_L(0); PG8_BAR; PG8_MMA(1, 0, At, B0); PG8_MMA(1, 1, At, B1); PG8_BAR; PG8_SCHED;
.LBB0_1390:
	s_setprio 1
	s_add_u32 s10, s6, 0xfffc0080
	s_addc_u32 s11, s7, -1
	s_add_i32 s39, 0, 0x10000
	s_cmp_eq_u32 s38, 12
	s_cselect_b32 s13, s95, s11
	s_cselect_b32 s12, s94, s10
	v_add_u32_e32 v144, s39, v146
	v_add_u32_e32 v232, s39, v231
	s_cselect_b32 s11, s97, s15
	s_cselect_b32 s10, s96, s14
	s_add_i32 s56, 0, 0x14000
	ds_read_b128 v[140:143], v144
	ds_read_b128 v[148:151], v232
	ds_read_b128 v[152:155], v144 offset:2048
	ds_read_b128 v[156:159], v232 offset:2048
	v_add_u32_e32 v144, s56, v146
	v_add_u32_e32 v233, s56, v231
	ds_read_b128 v[160:163], v144
	ds_read_b128 v[164:167], v233
	ds_read_b128 v[168:171], v144 offset:2048
	ds_read_b128 v[172:175], v233 offset:2048
	v_lshl_add_u64 v[144:145], s[6:7], 0, v[138:139]
	s_add_i32 m0, s53, 0xc000
	ds_read_b128 v[176:179], v147
	ds_read_b128 v[180:183], v230
	ds_read_b128 v[184:187], v147 offset:2048
	ds_read_b128 v[188:191], v230 offset:2048
	ds_read_b128 v[192:195], v147 offset:4096
	ds_read_b128 v[206:209], v230 offset:4096
	ds_read_b128 v[210:213], v147 offset:6144
	ds_read_b128 v[214:217], v230 offset:6144
	global_load_lds_dwordx4 v[144:145], off
	v_lshl_add_u64 v[144:145], s[6:7], 0, v[136:137]
	s_add_i32 m0, s53, 0xe000
	s_nop 0
	global_load_lds_dwordx4 v[144:145], off
	s_cmp_eq_u32 s38, -2
	s_cbranch_scc1 .Lfirstit_5
	s_waitcnt vmcnt(8)
.Lfirstit_5:
	s_waitcnt lgkmcnt(0)
	s_setprio 0
	s_barrier
	s_waitcnt lgkmcnt(0)
	v_mfma_f32_16x16x32_bf16 v[92:95], v[140:143], v[176:179], v[92:95]
	v_mfma_f32_16x16x32_bf16 v[88:91], v[152:155], v[176:179], v[88:91]
	v_mfma_f32_16x16x32_bf16 v[76:79], v[140:143], v[184:187], v[76:79]
	v_mfma_f32_16x16x32_bf16 v[72:75], v[152:155], v[184:187], v[72:75]
	v_mfma_f32_16x16x32_bf16 v[60:63], v[140:143], v[192:195], v[60:63]
	v_mfma_f32_16x16x32_bf16 v[56:59], v[152:155], v[192:195], v[56:59]
	v_mfma_f32_16x16x32_bf16 v[124:127], v[140:143], v[210:213], v[124:127]
	v_mfma_f32_16x16x32_bf16 v[120:123], v[152:155], v[210:213], v[120:123]
	v_mfma_f32_16x16x32_bf16 v[92:95], v[148:151], v[180:183], v[92:95]
	v_mfma_f32_16x16x32_bf16 v[88:91], v[156:159], v[180:183], v[88:91]
	v_mfma_f32_16x16x32_bf16 v[76:79], v[148:151], v[188:191], v[76:79]
	v_mfma_f32_16x16x32_bf16 v[72:75], v[156:159], v[188:191], v[72:75]
	v_mfma_f32_16x16x32_bf16 v[60:63], v[148:151], v[206:209], v[60:63]
	v_mfma_f32_16x16x32_bf16 v[56:59], v[156:159], v[206:209], v[56:59]
	v_mfma_f32_16x16x32_bf16 v[124:127], v[148:151], v[214:217], v[124:127]
	v_mfma_f32_16x16x32_bf16 v[120:123], v[156:159], v[214:217], v[120:123]
	v_mfma_f32_16x16x32_bf16 v[84:87], v[160:163], v[176:179], v[84:87]
	v_mfma_f32_16x16x32_bf16 v[80:83], v[168:171], v[176:179], v[80:83]
	v_mfma_f32_16x16x32_bf16 v[68:71], v[160:163], v[184:187], v[68:71]
	v_mfma_f32_16x16x32_bf16 v[64:67], v[168:171], v[184:187], v[64:67]
	v_mfma_f32_16x16x32_bf16 v[52:55], v[160:163], v[192:195], v[52:55]
	v_mfma_f32_16x16x32_bf16 v[48:51], v[168:171], v[192:195], v[48:51]
	v_mfma_f32_16x16x32_bf16 v[116:119], v[160:163], v[210:213], v[116:119]
	v_mfma_f32_16x16x32_bf16 v[112:115], v[168:171], v[210:213], v[112:115]
	v_mfma_f32_16x16x32_bf16 v[84:87], v[164:167], v[180:183], v[84:87]
	v_mfma_f32_16x16x32_bf16 v[80:83], v[172:175], v[180:183], v[80:83]
	v_mfma_f32_16x16x32_bf16 v[68:71], v[164:167], v[188:191], v[68:71]
	v_mfma_f32_16x16x32_bf16 v[64:67], v[172:175], v[188:191], v[64:67]
	v_mfma_f32_16x16x32_bf16 v[52:55], v[164:167], v[206:209], v[52:55]
	v_mfma_f32_16x16x32_bf16 v[48:51], v[172:175], v[206:209], v[48:51]
	v_mfma_f32_16x16x32_bf16 v[116:119], v[164:167], v[214:217], v[116:119]
	v_mfma_f32_16x16x32_bf16 v[112:115], v[172:175], v[214:217], v[112:115]
	s_barrier
	s_setprio 1
	s_add_i32 s39, s39, s52
	v_lshl_add_u64 v[144:145], s[10:11], 0, v[130:131]
	s_mov_b32 m0, s39
	ds_read_b128 v[176:179], v147 offset:16384
	ds_read_b128 v[180:183], v230 offset:16384
	ds_read_b128 v[184:187], v147 offset:18432
	ds_read_b128 v[188:191], v230 offset:18432
	ds_read_b128 v[192:195], v147 offset:20480
	ds_read_b128 v[206:209], v230 offset:20480
	ds_read_b128 v[210:213], v147 offset:22528
	ds_read_b128 v[214:217], v230 offset:22528
	global_load_lds_dwordx4 v[144:145], off
	s_add_i32 m0, s39, 0x2000
	s_add_u32 s48, s10, 0x40000
	v_lshl_add_u64 v[198:199], s[10:11], 0, v[134:135]
	s_addc_u32 s49, s11, 0
	s_add_i32 s39, s56, s52
	global_load_lds_dwordx4 v[198:199], off
	v_lshl_add_u64 v[200:201], s[48:49], 0, v[130:131]
	s_mov_b32 m0, s39
	v_lshl_add_u64 v[220:221], s[12:13], 0, v[132:133]
	global_load_lds_dwordx4 v[200:201], off
	v_lshl_add_u64 v[200:201], s[48:49], 0, v[134:135]
	s_add_i32 m0, s39, 0x2000
	s_nop 0
	global_load_lds_dwordx4 v[200:201], off
	v_lshl_add_u64 v[200:201], s[12:13], 0, v[128:129]
	s_mov_b32 m0, s53
	s_nop 0
	global_load_lds_dwordx4 v[200:201], off
	s_mov_b32 m0, s54
	s_nop 0
	global_load_lds_dwordx4 v[220:221], off
	s_waitcnt vmcnt(8)
	s_waitcnt lgkmcnt(0)
	s_setprio 0
	s_barrier
; #define PG8_STAGE(bufoff, gbase, voff) do { _Pragma("unroll") for (int _i = 0; _i < 2; ++_i) \
;         __builtin_amdgcn_global_load_lds((const unsigned*)((const char*)(gbase) + (voff)[_i]), (LAS unsigned*)(lds + (bufoff) + ldsw + _i * 8192), 16, 0, 0); } while (0)
; #define PG8_LDA(dst, b, h) do { _Pragma("unroll") for (int m = 0; m < 4; ++m) _Pragma("unroll") for (int k = 0; k < 2; ++k) dst[m][k] = *(const LAS bf16x8*)(lds + PG8_SA(b, h) + aoff + m * 2048 + k * 1024); } while (0)
; #define PG8_LDB(dst, b, h) do { _Pragma("unroll") for (int n = 0; n < 2; ++n) _Pragma("unroll") for (int k = 0; k < 2; ++k) dst[n][k] = *(const LAS bf16x8*)(lds + PG8_SB(b, h) + boff + n * 2048 + k * 1024); } while (0)
; #define PG8_MMA(ai, bj, At, Bt) do { __builtin_amdgcn_s_setprio(1); _Pragma("unroll") for (int m = 0; m < 4; ++m) _Pragma("unroll") for (int n = 0; n < 2; ++n) _Pragma("unroll") for (int k = 0; k < 2; ++k) \
;         acc[ai][bj][m][n] = __builtin_amdgcn_mfma_f32_16x16x32_bf16(Bt[n][k], At[m][k], acc[ai][bj][m][n], 0, 0, 0); __builtin_amdgcn_s_setprio(0); } while (0)
; #define PG8_WAIT_V(n) asm volatile("s_waitcnt vmcnt(" #n ")" ::: "memory")
; #define PG8_WAIT_L(n) asm volatile("s_waitcnt lgkmcnt(" #n ")" ::: "memory")
; #define PG8_BAR __builtin_amdgcn_s_barrier()
; #define PG8_SCHED __builtin_amdgcn_sched_barrier(0)
; template <class Epi, class Sched>
; __device__ __forceinline__ void gemm_phase(LAS unsigned char* lds, const GemmP g, const Sched& S, const Epi& E, int tid) {
;     ...
;             PG8_WAIT_V(8); PG8_WAIT_L(0); PG8_BAR; PG8_MMA(1, 0, At, B0); PG8_MMA(1, 1, At, B1); PG8_BAR; PG8_SCHED;
;             PG8_LDB(B0, 1, 0); PG8_LDB(B1, 1, 1); PG8_SCHED; PG8_LDA(At, 1, 0); PG8_STAGE(PG8_SA(0, 1), a2 + hstepA, voffA);
;             PG8_WAIT_V(8); PG8_WAIT_L(0); PG8_BAR; PG8_MMA(0, 0, At, B0); PG8_MMA(0, 1, At, B1); PG8_BAR; PG8_SCHED;
	s_waitcnt lgkmcnt(0)
	v_mfma_f32_16x16x32_bf16 v[44:47], v[140:143], v[176:179], v[44:47]
	v_mfma_f32_16x16x32_bf16 v[40:43], v[152:155], v[176:179], v[40:43]
	v_mfma_f32_16x16x32_bf16 v[28:31], v[140:143], v[184:187], v[28:31]
	v_mfma_f32_16x16x32_bf16 v[24:27], v[152:155], v[184:187], v[24:27]
	v_mfma_f32_16x16x32_bf16 v[12:15], v[140:143], v[192:195], v[12:15]
	v_mfma_f32_16x16x32_bf16 v[8:11], v[152:155], v[192:195], v[8:11]
	v_mfma_f32_16x16x32_bf16 v[108:111], v[140:143], v[210:213], v[108:111]
	v_mfma_f32_16x16x32_bf16 v[104:107], v[152:155], v[210:213], v[104:107]
	v_mfma_f32_16x16x32_bf16 v[44:47], v[148:151], v[180:183], v[44:47]
	v_mfma_f32_16x16x32_bf16 v[40:43], v[156:159], v[180:183], v[40:43]
	v_mfma_f32_16x16x32_bf16 v[28:31], v[148:151], v[188:191], v[28:31]
	v_mfma_f32_16x16x32_bf16 v[24:27], v[156:159], v[188:191], v[24:27]
	v_mfma_f32_16x16x32_bf16 v[12:15], v[148:151], v[206:209], v[12:15]
	v_mfma_f32_16x16x32_bf16 v[8:11], v[156:159], v[206:209], v[8:11]
	v_mfma_f32_16x16x32_bf16 v[108:111], v[148:151], v[214:217], v[108:111]
	v_mfma_f32_16x16x32_bf16 v[104:107], v[156:159], v[214:217], v[104:107]
	v_mfma_f32_16x16x32_bf16 v[36:39], v[160:163], v[176:179], v[36:39]
	v_mfma_f32_16x16x32_bf16 v[32:35], v[168:171], v[176:179], v[32:35]
	v_mfma_f32_16x16x32_bf16 v[20:23], v[160:163], v[184:187], v[20:23]
	v_mfma_f32_16x16x32_bf16 v[16:19], v[168:171], v[184:187], v[16:19]
	v_mfma_f32_16x16x32_bf16 v[4:7], v[160:163], v[192:195], v[4:7]
	v_mfma_f32_16x16x32_bf16 v[0:3], v[168:171], v[192:195], v[0:3]
	v_mfma_f32_16x16x32_bf16 v[100:103], v[160:163], v[210:213], v[100:103]
	v_mfma_f32_16x16x32_bf16 v[96:99], v[168:171], v[210:213], v[96:99]
	v_mfma_f32_16x16x32_bf16 v[36:39], v[164:167], v[180:183], v[36:39]
	v_mfma_f32_16x16x32_bf16 v[32:35], v[172:175], v[180:183], v[32:35]
	v_mfma_f32_16x16x32_bf16 v[20:23], v[164:167], v[188:191], v[20:23]
	v_mfma_f32_16x16x32_bf16 v[16:19], v[172:175], v[188:191], v[16:19]
	v_mfma_f32_16x16x32_bf16 v[4:7], v[164:167], v[206:209], v[4:7]
	v_mfma_f32_16x16x32_bf16 v[0:3], v[172:175], v[206:209], v[0:3]
	v_mfma_f32_16x16x32_bf16 v[100:103], v[164:167], v[214:217], v[100:103]
	v_mfma_f32_16x16x32_bf16 v[96:99], v[172:175], v[214:217], v[96:99]
	s_barrier
	s_setprio 1
	s_add_i32 s39, 0, 0x18000
	s_add_i32 s48, 0, 0x1c000
	v_add_u32_e32 v156, s39, v146
	v_add_u32_e32 v232, s39, v231
	v_add_u32_e32 v172, s48, v146
	v_add_u32_e32 v233, s48, v231
	ds_read_b128 v[140:143], v156
	ds_read_b128 v[148:151], v232
	ds_read_b128 v[152:155], v156 offset:2048
	ds_read_b128 v[156:159], v232 offset:2048
	ds_read_b128 v[160:163], v172
	ds_read_b128 v[164:167], v233
	ds_read_b128 v[168:171], v172 offset:2048
	ds_read_b128 v[172:175], v233 offset:2048
	s_add_u32 s12, s12, 0x40000
	s_addc_u32 s13, s13, 0
	s_mov_b32 m0, s58
	v_lshl_add_u64 v[222:223], s[12:13], 0, v[128:129]
	ds_read_b128 v[176:179], v147 offset:32768
	ds_read_b128 v[180:183], v230 offset:32768
	ds_read_b128 v[184:187], v147 offset:34816
	ds_read_b128 v[188:191], v230 offset:34816
	ds_read_b128 v[192:195], v147 offset:36864
	ds_read_b128 v[206:209], v230 offset:36864
	ds_read_b128 v[210:213], v147 offset:38912
	ds_read_b128 v[214:217], v230 offset:38912
	global_load_lds_dwordx4 v[222:223], off
	v_lshl_add_u64 v[222:223], s[12:13], 0, v[132:133]
	s_mov_b32 m0, s59
	s_nop 0
	global_load_lds_dwordx4 v[222:223], off
	s_waitcnt vmcnt(8)
	s_waitcnt lgkmcnt(0)
	s_setprio 0
	s_barrier
	s_waitcnt lgkmcnt(0)
	v_mfma_f32_16x16x32_bf16 v[92:95], v[140:143], v[176:179], v[92:95]
	v_mfma_f32_16x16x32_bf16 v[88:91], v[152:155], v[176:179], v[88:91]
	v_mfma_f32_16x16x32_bf16 v[76:79], v[140:143], v[184:187], v[76:79]
	v_mfma_f32_16x16x32_bf16 v[72:75], v[152:155], v[184:187], v[72:75]
	v_mfma_f32_16x16x32_bf16 v[60:63], v[140:143], v[192:195], v[60:63]
	v_mfma_f32_16x16x32_bf16 v[56:59], v[152:155], v[192:195], v[56:59]
	v_mfma_f32_16x16x32_bf16 v[124:127], v[140:143], v[210:213], v[124:127]
	v_mfma_f32_16x16x32_bf16 v[120:123], v[152:155], v[210:213], v[120:123]
	v_mfma_f32_16x16x32_bf16 v[92:95], v[148:151], v[180:183], v[92:95]
	v_mfma_f32_16x16x32_bf16 v[88:91], v[156:159], v[180:183], v[88:91]
	v_mfma_f32_16x16x32_bf16 v[76:79], v[148:151], v[188:191], v[76:79]
	v_mfma_f32_16x16x32_bf16 v[72:75], v[156:159], v[188:191], v[72:75]
	v_mfma_f32_16x16x32_bf16 v[60:63], v[148:151], v[206:209], v[60:63]
	v_mfma_f32_16x16x32_bf16 v[56:59], v[156:159], v[206:209], v[56:59]
	v_mfma_f32_16x16x32_bf16 v[124:127], v[148:151], v[214:217], v[124:127]
	v_mfma_f32_16x16x32_bf16 v[120:123], v[156:159], v[214:217], v[120:123]
	v_mfma_f32_16x16x32_bf16 v[84:87], v[160:163], v[176:179], v[84:87]
	v_mfma_f32_16x16x32_bf16 v[80:83], v[168:171], v[176:179], v[80:83]
	v_mfma_f32_16x16x32_bf16 v[68:71], v[160:163], v[184:187], v[68:71]
	v_mfma_f32_16x16x32_bf16 v[64:67], v[168:171], v[184:187], v[64:67]
	v_mfma_f32_16x16x32_bf16 v[52:55], v[160:163], v[192:195], v[52:55]
	v_mfma_f32_16x16x32_bf16 v[48:51], v[168:171], v[192:195], v[48:51]
	v_mfma_f32_16x16x32_bf16 v[116:119], v[160:163], v[210:213], v[116:119]
	v_mfma_f32_16x16x32_bf16 v[112:115], v[168:171], v[210:213], v[112:115]
	v_mfma_f32_16x16x32_bf16 v[84:87], v[164:167], v[180:183], v[84:87]
	v_mfma_f32_16x16x32_bf16 v[80:83], v[172:175], v[180:183], v[80:83]
	v_mfma_f32_16x16x32_bf16 v[68:71], v[164:167], v[188:191], v[68:71]
	v_mfma_f32_16x16x32_bf16 v[64:67], v[172:175], v[188:191], v[64:67]
	v_mfma_f32_16x16x32_bf16 v[52:55], v[164:167], v[206:209], v[52:55]
	v_mfma_f32_16x16x32_bf16 v[48:51], v[172:175], v[206:209], v[48:51]
	v_mfma_f32_16x16x32_bf16 v[116:119], v[164:167], v[214:217], v[116:119]
	v_mfma_f32_16x16x32_bf16 v[112:115], v[172:175], v[214:217], v[112:115]
	s_barrier
; #define PG8_STAGE(bufoff, gbase, voff) do { _Pragma("unroll") for (int _i = 0; _i < 2; ++_i) \
;         __builtin_amdgcn_global_load_lds((const unsigned*)((const char*)(gbase) + (voff)[_i]), (LAS unsigned*)(lds + (bufoff) + ldsw + _i * 8192), 16, 0, 0); } while (0)
; #define PG8_LDA(dst, b, h) do { _Pragma("unroll") for (int m = 0; m < 4; ++m) _Pragma("unroll") for (int k = 0; k < 2; ++k) dst[m][k] = *(const LAS bf16x8*)(lds + PG8_SA(b, h) + aoff + m * 2048 + k * 1024); } while (0)
; #define PG8_MMA(ai, bj, At, Bt) do { __builtin_amdgcn_s_setprio(1); _Pragma("unroll") for (int m = 0; m < 4; ++m) _Pragma("unroll") for (int n = 0; n < 2; ++n) _Pragma("unroll") for (int k = 0; k < 2; ++k) \
;         acc[ai][bj][m][n] = __builtin_amdgcn_mfma_f32_16x16x32_bf16(Bt[n][k], At[m][k], acc[ai][bj][m][n], 0, 0, 0); __builtin_amdgcn_s_setprio(0); } while (0)
; #define PG8_WAIT_V(n) asm volatile("s_waitcnt vmcnt(" #n ")" ::: "memory")
; #define PG8_WAIT_L(n) asm volatile("s_waitcnt lgkmcnt(" #n ")" ::: "memory")
; #define PG8_BAR __builtin_amdgcn_s_barrier()
; #define PG8_SCHED __builtin_amdgcn_sched_barrier(0)
; template <class Epi, class Sched>
; __device__ __forceinline__ void gemm_phase(LAS unsigned char* lds, const GemmP g, const Sched& S, const Epi& E, int tid) {
;     ...
;             PG8_LDA(At, 1, 1); PG8_STAGE(PG8_SB(1, 0), b3, voffB); PG8_STAGE(PG8_SB(1, 1), b3 + hstepB, voffB); PG8_STAGE(PG8_SA(1, 0), a3, voffA);
;             PG8_WAIT_V(8); PG8_WAIT_L(0); PG8_BAR; PG8_MMA(1, 0, At, B0); PG8_MMA(1, 1, At, B1); PG8_BAR; PG8_SCHED;
;         }
;         if (wr == 0) PG8_BAR;
	s_setprio 1
	s_add_i32 s12, s39, s52
	v_lshl_add_u64 v[144:145], v[144:145], 0, s[80:81]
	s_mov_b32 m0, s12
	ds_read_b128 v[176:179], v147 offset:49152
	ds_read_b128 v[180:183], v230 offset:49152
	ds_read_b128 v[184:187], v147 offset:51200
	ds_read_b128 v[188:191], v230 offset:51200
	ds_read_b128 v[192:195], v147 offset:53248
	ds_read_b128 v[206:209], v230 offset:53248
	ds_read_b128 v[210:213], v147 offset:55296
	ds_read_b128 v[214:217], v230 offset:55296
	global_load_lds_dwordx4 v[144:145], off
	s_add_i32 m0, s12, 0x2000
	s_add_u32 s10, s10, 0x40080
	v_lshl_add_u64 v[144:145], v[198:199], 0, s[80:81]
	s_addc_u32 s11, s11, 0
	s_add_i32 s12, s48, s52
	global_load_lds_dwordx4 v[144:145], off
	v_lshl_add_u64 v[144:145], s[10:11], 0, v[130:131]
	s_mov_b32 m0, s12
	s_nop 0
	global_load_lds_dwordx4 v[144:145], off
	v_lshl_add_u64 v[144:145], s[10:11], 0, v[134:135]
	s_add_i32 m0, s12, 0x2000
	s_nop 0
	global_load_lds_dwordx4 v[144:145], off
	v_lshl_add_u64 v[144:145], v[200:201], 0, s[80:81]
	s_mov_b32 m0, s89
	s_nop 0
	global_load_lds_dwordx4 v[144:145], off
	v_lshl_add_u64 v[144:145], v[220:221], 0, s[80:81]
	s_mov_b32 m0, s64
	s_nop 0
	global_load_lds_dwordx4 v[144:145], off
	s_waitcnt vmcnt(8)
	s_waitcnt lgkmcnt(0)
	s_setprio 0
	s_barrier
	s_waitcnt lgkmcnt(0)
	v_mfma_f32_16x16x32_bf16 v[44:47], v[140:143], v[176:179], v[44:47]
	v_mfma_f32_16x16x32_bf16 v[40:43], v[152:155], v[176:179], v[40:43]
	v_mfma_f32_16x16x32_bf16 v[28:31], v[140:143], v[184:187], v[28:31]
	v_mfma_f32_16x16x32_bf16 v[24:27], v[152:155], v[184:187], v[24:27]
	v_mfma_f32_16x16x32_bf16 v[12:15], v[140:143], v[192:195], v[12:15]
	v_mfma_f32_16x16x32_bf16 v[8:11], v[152:155], v[192:195], v[8:11]
	v_mfma_f32_16x16x32_bf16 v[108:111], v[140:143], v[210:213], v[108:111]
	v_mfma_f32_16x16x32_bf16 v[104:107], v[152:155], v[210:213], v[104:107]
	v_mfma_f32_16x16x32_bf16 v[44:47], v[148:151], v[180:183], v[44:47]
	v_mfma_f32_16x16x32_bf16 v[40:43], v[156:159], v[180:183], v[40:43]
	v_mfma_f32_16x16x32_bf16 v[28:31], v[148:151], v[188:191], v[28:31]
	v_mfma_f32_16x16x32_bf16 v[24:27], v[156:159], v[188:191], v[24:27]
	v_mfma_f32_16x16x32_bf16 v[12:15], v[148:151], v[206:209], v[12:15]
	v_mfma_f32_16x16x32_bf16 v[8:11], v[156:159], v[206:209], v[8:11]
	v_mfma_f32_16x16x32_bf16 v[108:111], v[148:151], v[214:217], v[108:111]
	v_mfma_f32_16x16x32_bf16 v[104:107], v[156:159], v[214:217], v[104:107]
	v_mfma_f32_16x16x32_bf16 v[36:39], v[160:163], v[176:179], v[36:39]
	v_mfma_f32_16x16x32_bf16 v[32:35], v[168:171], v[176:179], v[32:35]
	v_mfma_f32_16x16x32_bf16 v[20:23], v[160:163], v[184:187], v[20:23]
	v_mfma_f32_16x16x32_bf16 v[16:19], v[168:171], v[184:187], v[16:19]
	v_mfma_f32_16x16x32_bf16 v[4:7], v[160:163], v[192:195], v[4:7]
	v_mfma_f32_16x16x32_bf16 v[0:3], v[168:171], v[192:195], v[0:3]
	v_mfma_f32_16x16x32_bf16 v[100:103], v[160:163], v[210:213], v[100:103]
	v_mfma_f32_16x16x32_bf16 v[96:99], v[168:171], v[210:213], v[96:99]
	v_mfma_f32_16x16x32_bf16 v[36:39], v[164:167], v[180:183], v[36:39]
	v_mfma_f32_16x16x32_bf16 v[32:35], v[172:175], v[180:183], v[32:35]
	v_mfma_f32_16x16x32_bf16 v[20:23], v[164:167], v[188:191], v[20:23]
	v_mfma_f32_16x16x32_bf16 v[16:19], v[172:175], v[188:191], v[16:19]
	v_mfma_f32_16x16x32_bf16 v[4:7], v[164:167], v[206:209], v[4:7]
	v_mfma_f32_16x16x32_bf16 v[0:3], v[172:175], v[206:209], v[0:3]
	v_mfma_f32_16x16x32_bf16 v[100:103], v[164:167], v[214:217], v[100:103]
	v_mfma_f32_16x16x32_bf16 v[96:99], v[172:175], v[214:217], v[96:99]
	s_barrier
	s_add_i32 s38, s38, 2
	s_add_u32 s14, s14, 0x100
	s_addc_u32 s15, s15, 0
	s_add_u32 s6, s6, 0x100
	s_addc_u32 s7, s7, 0
	s_cmp_gt_u32 s38, 13
	s_cbranch_scc0 .LBB0_1390
	s_and_b64 vcc, exec, s[2:3]
	s_cbranch_vccz .LBB0_1393
	s_barrier

; #define GAS __attribute__((address_space(1)))
; #define LAS __attribute__((address_space(3)))
; __device__ __forceinline__ unsigned pk_bf16(float lo, float hi) { f32x2_t v = {lo, hi}; bf16x2_t b = __builtin_convertvector(v, bf16x2_t); return __builtin_bit_cast(unsigned, b); }
;     __device__ __forceinline__ void operator()(EPI_ARGS) const {
;     ...
;         for (int ai = 0; ai < 2; ++ai) {
;             const int brow0 = u.row0 + ai * HALF + wr * 64;
;             const int sb = samp ? ((brow0 - MP) >> 6) : 0, pred = (ai * 2 + wr) > 0 ? (ai * 2 + wr - 1) : 0;
;             const bool use_x = !samp && (brow0 & (SEQ - 1)) != 0 && (ai | wr) != 0;
;             const int hsel = fr >= 14 ? fr - 14 : 0;
;             unsigned pk[4][4];
; #pragma unroll
;             for (int q = 0; q < 4; ++q) {
;                 const int c2 = ch + 2 * q;
;                 const f32x2_t bg = {BG[q >> 1][2 * (q & 1)], BG[q >> 1][2 * (q & 1) + 1]}, bv = {BV[q >> 1][2 * (q & 1)], BV[q >> 1][2 * (q & 1) + 1]};
;                 const LAS float* xp = X + (pred * 2 + hsel) * 256 + cl + 2 * q;
;                 const f32x2_t xgv = *(const LAS f32x2_t*)xp, xvv = *(const LAS f32x2_t*)(xp + HALF);
;                 unsigned hg = use_x ? pk_bf16(xgv.x, xgv.y) : 0u, hv = use_x ? pk_bf16(xvv.x, xvv.y) : 0u;
;                 if (samp) { const float* sp = sfs + ((size_t)sb * 2 + hsel) * FF2 + c2; const f32x2_t sgv = *(const GAS f32x2_t*)sp, svv = *(const GAS f32x2_t*)(sp + FF); hg = pk_bf16(sgv.x, sgv.y); hv = pk_bf16(svv.x, svv.y); }
.LBB0_1409:
	s_add_i32 s10, s62, 0xffff0000
	s_ashr_i32 s10, s10, 6
	v_lshl_or_b32 v102, s10, 1, v97
	v_mov_b64_e32 v[64:65], s[26:27]
	s_movk_i32 s10, 0x5800
	v_mad_i64_i32 v[64:65], s[10:11], v102, s10, v[64:65]
	v_cndmask_b32_e64 v102, 0, 1, s[48:49]
	v_cmp_ne_u32_e64 s[10:11], 1, v102
	s_andn2_b64 vcc, exec, s[48:49]
	v_lshl_add_u64 v[64:65], v[142:143], 2, v[64:65]
	s_cbranch_vccnz .LBB0_1411
	s_waitcnt lgkmcnt(0)
	v_add_co_u32_e32 v66, vcc, 0x2000, v64
	s_nop 1
	v_addc_co_u32_e32 v67, vcc, 0, v65, vcc
	global_load_dwordx2 v[102:103], v[64:65], off
	global_load_dwordx2 v[238:239], v[64:65], off offset:8
	global_load_dwordx2 v[240:241], v[64:65], off offset:16
	global_load_dwordx2 v[242:243], v[64:65], off offset:24
	global_load_dwordx2 v[244:245], v[66:67], off offset:3080
	global_load_dwordx2 v[246:247], v[66:67], off offset:3088
	global_load_dwordx2 v[248:249], v[66:67], off offset:3096
	s_nop 0
	global_load_dwordx2 v[66:67], v[66:67], off offset:3072
	s_waitcnt vmcnt(7)
	v_cvt_pk_bf16_f32 v99, v102, v103
	s_waitcnt vmcnt(0)
	v_cvt_pk_bf16_f32 v66, v66, v67
	s_branch .LBB0_1412

; #define GAS __attribute__((address_space(1)))
; #define LAS __attribute__((address_space(3)))
; __device__ __forceinline__ unsigned pk_bf16(float lo, float hi) { f32x2_t v = {lo, hi}; bf16x2_t b = __builtin_convertvector(v, bf16x2_t); return __builtin_bit_cast(unsigned, b); }
;     __device__ __forceinline__ void operator()(EPI_ARGS) const {
;     ...
;             for (int q = 0; q < 4; ++q) {
;                 const int c2 = ch + 2 * q;
;                 const f32x2_t bg = {BG[q >> 1][2 * (q & 1)], BG[q >> 1][2 * (q & 1) + 1]}, bv = {BV[q >> 1][2 * (q & 1)], BV[q >> 1][2 * (q & 1) + 1]};
;                 const LAS float* xp = X + (pred * 2 + hsel) * 256 + cl + 2 * q;
;                 const f32x2_t xgv = *(const LAS f32x2_t*)xp, xvv = *(const LAS f32x2_t*)(xp + HALF);
;                 unsigned hg = use_x ? pk_bf16(xgv.x, xgv.y) : 0u, hv = use_x ? pk_bf16(xvv.x, xvv.y) : 0u;
;                 if (samp) { const float* sp = sfs + ((size_t)sb * 2 + hsel) * FF2 + c2; const f32x2_t sgv = *(const GAS f32x2_t*)sp, svv = *(const GAS f32x2_t*)(sp + FF); hg = pk_bf16(sgv.x, sgv.y); hv = pk_bf16(svv.x, svv.y); }
.LBB0_1414:
	s_and_b64 vcc, exec, s[10:11]
	s_cbranch_vccnz .LBB0_1416
	s_waitcnt lgkmcnt(0)
	v_cvt_pk_bf16_f32 v150, v238, v239
	v_cvt_pk_bf16_f32 v66, v244, v245
	s_branch .LBB0_1417

; #define GAS __attribute__((address_space(1)))
; #define LAS __attribute__((address_space(3)))
; __device__ __forceinline__ unsigned pk_bf16(float lo, float hi) { f32x2_t v = {lo, hi}; bf16x2_t b = __builtin_convertvector(v, bf16x2_t); return __builtin_bit_cast(unsigned, b); }
;     __device__ __forceinline__ void operator()(EPI_ARGS) const {
;     ...
;             for (int q = 0; q < 4; ++q) {
;                 const int c2 = ch + 2 * q;
;                 const f32x2_t bg = {BG[q >> 1][2 * (q & 1)], BG[q >> 1][2 * (q & 1) + 1]}, bv = {BV[q >> 1][2 * (q & 1)], BV[q >> 1][2 * (q & 1) + 1]};
;                 const LAS float* xp = X + (pred * 2 + hsel) * 256 + cl + 2 * q;
;                 const f32x2_t xgv = *(const LAS f32x2_t*)xp, xvv = *(const LAS f32x2_t*)(xp + HALF);
;                 unsigned hg = use_x ? pk_bf16(xgv.x, xgv.y) : 0u, hv = use_x ? pk_bf16(xvv.x, xvv.y) : 0u;
;                 if (samp) { const float* sp = sfs + ((size_t)sb * 2 + hsel) * FF2 + c2; const f32x2_t sgv = *(const GAS f32x2_t*)sp, svv = *(const GAS f32x2_t*)(sp + FF); hg = pk_bf16(sgv.x, sgv.y); hv = pk_bf16(svv.x, svv.y); }
.LBB0_1419:
	s_and_b64 vcc, exec, s[10:11]
	s_cbranch_vccnz .LBB0_1421
	s_waitcnt lgkmcnt(0)
	v_cvt_pk_bf16_f32 v150, v240, v241
	v_cvt_pk_bf16_f32 v66, v246, v247
	s_branch .LBB0_1422

; #define GAS __attribute__((address_space(1)))
; #define LAS __attribute__((address_space(3)))
; __device__ __forceinline__ unsigned pk_bf16(float lo, float hi) { f32x2_t v = {lo, hi}; bf16x2_t b = __builtin_convertvector(v, bf16x2_t); return __builtin_bit_cast(unsigned, b); }
;     __device__ __forceinline__ void operator()(EPI_ARGS) const {
;     ...
;             for (int q = 0; q < 4; ++q) {
;                 const int c2 = ch + 2 * q;
;                 const f32x2_t bg = {BG[q >> 1][2 * (q & 1)], BG[q >> 1][2 * (q & 1) + 1]}, bv = {BV[q >> 1][2 * (q & 1)], BV[q >> 1][2 * (q & 1) + 1]};
;                 const LAS float* xp = X + (pred * 2 + hsel) * 256 + cl + 2 * q;
;                 const f32x2_t xgv = *(const LAS f32x2_t*)xp, xvv = *(const LAS f32x2_t*)(xp + HALF);
;                 unsigned hg = use_x ? pk_bf16(xgv.x, xgv.y) : 0u, hv = use_x ? pk_bf16(xvv.x, xvv.y) : 0u;
;                 if (samp) { const float* sp = sfs + ((size_t)sb * 2 + hsel) * FF2 + c2; const f32x2_t sgv = *(const GAS f32x2_t*)sp, svv = *(const GAS f32x2_t*)(sp + FF); hg = pk_bf16(sgv.x, sgv.y); hv = pk_bf16(svv.x, svv.y); }
.LBB0_1424:
	s_and_b64 vcc, exec, s[10:11]
	s_cbranch_vccnz .LBB0_1426
	s_waitcnt lgkmcnt(0)
	v_cvt_pk_bf16_f32 v150, v242, v243
	v_cvt_pk_bf16_f32 v67, v248, v249
	s_branch .LBB0_1427

; #define GAS __attribute__((address_space(1)))
; #define LAS __attribute__((address_space(3)))
; __device__ __forceinline__ unsigned pk_bf16(float lo, float hi) { f32x2_t v = {lo, hi}; bf16x2_t b = __builtin_convertvector(v, bf16x2_t); return __builtin_bit_cast(unsigned, b); }
;     __device__ __forceinline__ void operator()(EPI_ARGS) const {
;     ...
;         for (int ai = 0; ai < 2; ++ai) {
;             const int brow0 = u.row0 + ai * HALF + wr * 64;
;             const int sb = samp ? ((brow0 - MP) >> 6) : 0, pred = (ai * 2 + wr) > 0 ? (ai * 2 + wr - 1) : 0;
;             const bool use_x = !samp && (brow0 & (SEQ - 1)) != 0 && (ai | wr) != 0;
;             const int hsel = fr >= 14 ? fr - 14 : 0;
;             unsigned pk[4][4];
; #pragma unroll
;             for (int q = 0; q < 4; ++q) {
;                 const int c2 = ch + 2 * q;
;                 const f32x2_t bg = {BG[q >> 1][2 * (q & 1)], BG[q >> 1][2 * (q & 1) + 1]}, bv = {BV[q >> 1][2 * (q & 1)], BV[q >> 1][2 * (q & 1) + 1]};
;                 const LAS float* xp = X + (pred * 2 + hsel) * 256 + cl + 2 * q;
;                 const f32x2_t xgv = *(const LAS f32x2_t*)xp, xvv = *(const LAS f32x2_t*)(xp + HALF);
;                 unsigned hg = use_x ? pk_bf16(xgv.x, xgv.y) : 0u, hv = use_x ? pk_bf16(xvv.x, xvv.y) : 0u;
;                 if (samp) { const float* sp = sfs + ((size_t)sb * 2 + hsel) * FF2 + c2; const f32x2_t sgv = *(const GAS f32x2_t*)sp, svv = *(const GAS f32x2_t*)(sp + FF); hg = pk_bf16(sgv.x, sgv.y); hv = pk_bf16(svv.x, svv.y); }
.LBB0_1429:
	s_add_i32 s62, s62, 0xffff0080
	s_ashr_i32 s39, s62, 6
	v_lshl_or_b32 v69, s39, 1, v97
	v_mov_b64_e32 v[64:65], s[26:27]
	s_movk_i32 s39, 0x5800
	v_mad_i64_i32 v[64:65], s[48:49], v69, s39, v[64:65]
	s_and_b64 vcc, exec, s[10:11]
	v_lshl_add_u64 v[64:65], v[142:143], 2, v[64:65]
	s_cbranch_vccnz .LBB0_1431
	s_waitcnt lgkmcnt(0)
	v_add_co_u32_e32 v66, vcc, 0x2000, v64
	s_nop 1
	v_addc_co_u32_e32 v67, vcc, 0, v65, vcc
	global_load_dwordx2 v[68:69], v[64:65], off
	global_load_dwordx2 v[238:239], v[64:65], off offset:8
	global_load_dwordx2 v[240:241], v[64:65], off offset:16
	global_load_dwordx2 v[242:243], v[64:65], off offset:24
	global_load_dwordx2 v[244:245], v[66:67], off offset:3080
	global_load_dwordx2 v[246:247], v[66:67], off offset:3088
	global_load_dwordx2 v[248:249], v[66:67], off offset:3096
	s_nop 0
	global_load_dwordx2 v[66:67], v[66:67], off offset:3072
	s_waitcnt vmcnt(7)
	v_cvt_pk_bf16_f32 v68, v68, v69
	s_waitcnt vmcnt(0)
	v_cvt_pk_bf16_f32 v66, v66, v67
	s_branch .LBB0_1432

; #define GAS __attribute__((address_space(1)))
; #define LAS __attribute__((address_space(3)))
; __device__ __forceinline__ unsigned pk_bf16(float lo, float hi) { f32x2_t v = {lo, hi}; bf16x2_t b = __builtin_convertvector(v, bf16x2_t); return __builtin_bit_cast(unsigned, b); }
;     __device__ __forceinline__ void operator()(EPI_ARGS) const {
;     ...
;             for (int q = 0; q < 4; ++q) {
;                 const int c2 = ch + 2 * q;
;                 const f32x2_t bg = {BG[q >> 1][2 * (q & 1)], BG[q >> 1][2 * (q & 1) + 1]}, bv = {BV[q >> 1][2 * (q & 1)], BV[q >> 1][2 * (q & 1) + 1]};
;                 const LAS float* xp = X + (pred * 2 + hsel) * 256 + cl + 2 * q;
;                 const f32x2_t xgv = *(const LAS f32x2_t*)xp, xvv = *(const LAS f32x2_t*)(xp + HALF);
;                 unsigned hg = use_x ? pk_bf16(xgv.x, xgv.y) : 0u, hv = use_x ? pk_bf16(xvv.x, xvv.y) : 0u;
;                 if (samp) { const float* sp = sfs + ((size_t)sb * 2 + hsel) * FF2 + c2; const f32x2_t sgv = *(const GAS f32x2_t*)sp, svv = *(const GAS f32x2_t*)(sp + FF); hg = pk_bf16(sgv.x, sgv.y); hv = pk_bf16(svv.x, svv.y); }
.LBB0_1434:
	s_and_b64 vcc, exec, s[10:11]
	s_cbranch_vccnz .LBB0_1436
	s_waitcnt lgkmcnt(0)
	v_cvt_pk_bf16_f32 v69, v238, v239
	v_cvt_pk_bf16_f32 v66, v244, v245
	s_branch .LBB0_1437

; #define GAS __attribute__((address_space(1)))
; #define LAS __attribute__((address_space(3)))
; __device__ __forceinline__ unsigned pk_bf16(float lo, float hi) { f32x2_t v = {lo, hi}; bf16x2_t b = __builtin_convertvector(v, bf16x2_t); return __builtin_bit_cast(unsigned, b); }
;     __device__ __forceinline__ void operator()(EPI_ARGS) const {
;     ...
;             for (int q = 0; q < 4; ++q) {
;                 const int c2 = ch + 2 * q;
;                 const f32x2_t bg = {BG[q >> 1][2 * (q & 1)], BG[q >> 1][2 * (q & 1) + 1]}, bv = {BV[q >> 1][2 * (q & 1)], BV[q >> 1][2 * (q & 1) + 1]};
;                 const LAS float* xp = X + (pred * 2 + hsel) * 256 + cl + 2 * q;
;                 const f32x2_t xgv = *(const LAS f32x2_t*)xp, xvv = *(const LAS f32x2_t*)(xp + HALF);
;                 unsigned hg = use_x ? pk_bf16(xgv.x, xgv.y) : 0u, hv = use_x ? pk_bf16(xvv.x, xvv.y) : 0u;
;                 if (samp) { const float* sp = sfs + ((size_t)sb * 2 + hsel) * FF2 + c2; const f32x2_t sgv = *(const GAS f32x2_t*)sp, svv = *(const GAS f32x2_t*)(sp + FF); hg = pk_bf16(sgv.x, sgv.y); hv = pk_bf16(svv.x, svv.y); }
.LBB0_1439:
	s_and_b64 vcc, exec, s[10:11]
	s_cbranch_vccnz .LBB0_1441
	s_waitcnt lgkmcnt(0)
	v_cvt_pk_bf16_f32 v74, v240, v241
	v_cvt_pk_bf16_f32 v66, v246, v247
	s_branch .LBB0_1442

; #define GAS __attribute__((address_space(1)))
; #define LAS __attribute__((address_space(3)))
; __device__ __forceinline__ unsigned pk_bf16(float lo, float hi) { f32x2_t v = {lo, hi}; bf16x2_t b = __builtin_convertvector(v, bf16x2_t); return __builtin_bit_cast(unsigned, b); }
;     __device__ __forceinline__ void operator()(EPI_ARGS) const {
;     ...
;             for (int q = 0; q < 4; ++q) {
;                 const int c2 = ch + 2 * q;
;                 const f32x2_t bg = {BG[q >> 1][2 * (q & 1)], BG[q >> 1][2 * (q & 1) + 1]}, bv = {BV[q >> 1][2 * (q & 1)], BV[q >> 1][2 * (q & 1) + 1]};
;                 const LAS float* xp = X + (pred * 2 + hsel) * 256 + cl + 2 * q;
;                 const f32x2_t xgv = *(const LAS f32x2_t*)xp, xvv = *(const LAS f32x2_t*)(xp + HALF);
;                 unsigned hg = use_x ? pk_bf16(xgv.x, xgv.y) : 0u, hv = use_x ? pk_bf16(xvv.x, xvv.y) : 0u;
;                 if (samp) { const float* sp = sfs + ((size_t)sb * 2 + hsel) * FF2 + c2; const f32x2_t sgv = *(const GAS f32x2_t*)sp, svv = *(const GAS f32x2_t*)(sp + FF); hg = pk_bf16(sgv.x, sgv.y); hv = pk_bf16(svv.x, svv.y); }
.LBB0_1444:
	s_and_b64 vcc, exec, s[10:11]
	s_cbranch_vccnz .LBB0_1446
	s_waitcnt lgkmcnt(0)
	v_cvt_pk_bf16_f32 v121, v242, v243
	v_cvt_pk_bf16_f32 v67, v248, v249
	s_branch .LBB0_1447
